# 9 layer-1 conversion tiles per idle workgroup in the sample l0 mixer phase (96 left in the prompt phase) + qk-prep DPP reductions
# speedup vs baseline: 1.0038x; 1.0023x over previous
.LBB0_225:
	v_writelane_b32 v255, s12, 6
	s_andn2_b64 vcc, exec, s[4:5]
	s_nop 0
	v_writelane_b32 v255, s13, 7
	v_writelane_b32 v255, s0, 10
	s_nop 1
	v_writelane_b32 v255, s1, 11
	v_writelane_b32 v255, s77, 12
	s_cbranch_vccnz .LBB0_308
	s_cmp_eq_u32 s6, 14
	s_cselect_b32 vcc_lo, 1, 0
	v_writelane_b32 v255, vcc_lo, 30
	s_add_i32 s20, s6, 18
	s_cmp_gt_u32 s20, 38
	s_cselect_b64 s[0:1], -1, 0
	s_lshl_b32 s4, s74, 2
	v_writelane_b32 v255, s0, 4
	s_ashr_i32 s5, s4, 31
	s_lshl_b64 s[4:5], s[4:5], 2
	v_writelane_b32 v255, s1, 5
	v_readlane_b32 s0, v252, 24
	s_add_u32 s4, s0, s4
	v_readlane_b32 s0, v252, 25
	s_addc_u32 s5, s0, s5
	v_writelane_b32 v255, s4, 13
	s_cmp_lt_u32 s20, 39
	s_mov_b32 s0, 0x4c25000
	v_writelane_b32 v255, s5, 14
	s_movk_i32 s4, 0x660
	v_readlane_b32 s16, v255, 6
	v_readlane_b32 s17, v255, 7
	s_cselect_b32 s34, s4, 0x600
	s_and_b64 s[4:5], s[16:17], exec
	v_readlane_b32 s36, v252, 4
	s_cselect_b32 s4, s0, 0x9c25000
	v_readlane_b32 s50, v252, 18
	v_readlane_b32 s51, v252, 19
	s_add_u32 s0, s50, s4
	s_addc_u32 s1, s51, 0
	v_writelane_b32 v255, s0, 8
	s_and_b64 s[4:5], s[16:17], exec
	v_readlane_b32 s52, v253, 8
	v_writelane_b32 v255, s1, 9
	s_mov_b32 s0, 0xfd25000
	s_cselect_b32 s4, s0, 0x6425000
	s_add_u32 s0, s50, s4
	s_addc_u32 s1, s51, 0
	v_writelane_b32 v255, s0, 15
	v_readlane_b32 s66, v253, 22
	v_readlane_b32 s67, v253, 23
	v_writelane_b32 v255, s1, 16
	v_readlane_b32 s24, v252, 34
	v_readlane_b32 s0, v255, 2
	s_lshl_b32 s4, s0, 7
	s_ashr_i32 s5, s4, 31
	s_lshl_b64 s[4:5], s[4:5], 2
	v_readlane_b32 s1, v255, 3
	s_mov_b32 s26, s0
	s_add_u32 s0, s66, s4
	s_addc_u32 s1, s67, s5
	v_writelane_b32 v255, s0, 17
	s_and_b64 s[20:21], s[16:17], exec
	s_cselect_b32 s35, 4, 64
	v_writelane_b32 v255, s1, 18
	s_movk_i32 s0, 0x100
	s_cselect_b32 s13, s0, 0x1100
	s_cselect_b32 s14, 8, 12
	s_ashr_i32 s27, s26, 31
	s_lshl_b32 s0, s13, 8
	s_lshl_b32 s15, s13, 7
	s_lshr_b32 s77, s13, 6
	s_lshl_b32 s22, s13, 6
	s_lshl_b64 s[20:21], s[26:27], 2
	v_writelane_b32 v255, s0, 19
	v_readlane_b32 s25, v252, 35
	s_add_u32 s0, s24, s20
	v_cvt_f32_ubyte0_e32 v0, s35
	s_addc_u32 s1, s25, s21
	v_rcp_iflag_f32_e32 v0, v0
	s_add_u32 s20, s50, s20
	v_writelane_b32 v255, s0, 20
	s_addc_u32 s21, s51, s21
	v_readlane_b32 s38, v252, 6
	v_writelane_b32 v255, s1, 21
	s_add_u32 s0, s20, 0x4b24008
	s_addc_u32 s1, s21, 0
	v_mul_f32_e32 v0, 0x4f7ffffe, v0
	v_readlane_b32 s39, v252, 7
	s_add_u32 s28, s38, s4
	v_cvt_u32_f32_e32 v0, v0
	s_addc_u32 s29, s39, s5
	s_and_b64 s[4:5], s[16:17], exec
	s_cselect_b32 s16, 1, 16
	v_readfirstlane_b32 s5, v0
	v_cvt_f32_ubyte0_e32 v0, s16
	v_rcp_iflag_f32_e32 v0, v0
	v_writelane_b32 v255, s0, 22
	s_sub_i32 s4, 0, s35
	s_mul_i32 s4, s4, s5
	v_mul_f32_e32 v0, 0x4f7ffffe, v0
	v_cvt_u32_f32_e32 v0, v0
	v_writelane_b32 v255, s1, 23
	s_mov_b32 s0, s26
	v_writelane_b32 v255, s0, 2
	s_mul_hi_u32 s4, s5, s4
	s_mov_b32 s75, 0x60000
	v_writelane_b32 v255, s1, 3
	s_add_i32 s0, s5, s4
	s_sub_i32 s4, 0, s16
	v_readfirstlane_b32 s5, v0
	s_mul_i32 s4, s4, s5
	s_mul_hi_u32 s4, s5, s4
	s_mov_b32 s76, 0x8000
	s_mov_b32 s23, s95
	s_lshl_b32 s17, s26, 1
	v_writelane_b32 v255, s0, 24
	s_add_i32 s0, s5, s4
	s_sub_i32 s12, 0, s77
	s_mov_b32 s96, s71
	v_readlane_b32 s37, v252, 5
	v_readlane_b32 s40, v252, 8
	v_readlane_b32 s41, v252, 9
	v_readlane_b32 s42, v252, 10
	v_readlane_b32 s43, v252, 11
	v_readlane_b32 s44, v252, 12
	v_readlane_b32 s45, v252, 13
	v_readlane_b32 s46, v252, 14
	v_readlane_b32 s47, v252, 15
	v_readlane_b32 s48, v252, 16
	v_readlane_b32 s49, v252, 17
	v_readlane_b32 s53, v253, 9
	v_readlane_b32 s54, v253, 10
	v_readlane_b32 s55, v253, 11
	v_readlane_b32 s56, v253, 12
	v_readlane_b32 s57, v253, 13
	v_readlane_b32 s58, v253, 14
	v_readlane_b32 s59, v253, 15
	v_readlane_b32 s60, v253, 16
	v_readlane_b32 s61, v253, 17
	v_readlane_b32 s62, v253, 18
	v_readlane_b32 s63, v253, 19
	v_readlane_b32 s64, v253, 20
	v_readlane_b32 s65, v253, 21
	s_branch .LBB0_229

.Lattn_static:
	s_waitcnt lgkmcnt(0)
	ds_read_b32 v2, v196 offset:4
	v_readlane_b32 s99, v255, 12
	s_waitcnt lgkmcnt(0)
	v_readfirstlane_b32 s24, v2
	s_nop 3
	s_and_b32 s25, s99, 7
	s_lshl_b32 s25, s25, 6
	s_lshr_b32 s26, s99, 3
	s_or_b32 s25, s25, s26
	s_add_i32 s25, s25, 0x100
	s_cmpk_lt_u32 s99, 0x100
	s_cselect_b32 s26, 0, 1
	s_add_i32 s26, s26, s24
	s_add_i32 s24, s24, 1
	s_cmp_eq_u32 s26, 1
	s_cselect_b32 s98, s25, 0x300
	s_cmp_eq_u32 s26, 0
	s_cselect_b32 s98, s99, s98
	v_readlane_b32 vcc_hi, v255, 30
	s_nop 3
	s_cmpk_lt_u32 s99, 0x100
	s_cbranch_scc1 .Lcv_no
	s_cmp_eq_u32 vcc_hi, 0
	s_cbranch_scc1 .Lcv_no
	s_cmp_lt_u32 s26, 2
	s_cbranch_scc1 .Lcv_no
	s_cmp_gt_u32 s26, 10
	s_cbranch_scc1 .Lcv_no
	s_sub_u32 vcc_lo, s26, 2
	s_lshl_b32 vcc_lo, vcc_lo, 8
	s_add_u32 vcc_lo, s99, vcc_lo
	s_add_u32 vcc_lo, vcc_lo, 0x360
	s_cmpk_ge_u32 vcc_lo, 0xd60
	s_cbranch_scc1 .Lcv_no
	s_mov_b32 s98, vcc_lo
	s_branch .Lcv_keep
